# DSA tile: exp/sum/pack of the second 32-key half interleaved between the PV MFMAs of the first half in the same wave; V fragments of the first half read before the first-half exp block
# speedup vs baseline: 1.0151x; 1.0003x over previous
; template <bool MASKED>
; __device__ __forceinline__ void softmax_tile(f32x16& s0, f32x16& s1, float& m, float& l, float& alpha, unsigned mlo, unsigned mhi, bf16x8 (&pk)[4]) {
;     ...
;     const float mn = fmaxf(m, mx);
;     alpha = __builtin_amdgcn_exp2f(m - mn); m = mn;
.LBB0_1176:
	s_andn2_b64 vcc, exec, s[12:13]
	s_cbranch_vccnz .LBB0_1180
	s_mul_i32 s12, s17, 0xa000
	s_add_i32 s12, s12, 0
	v_add_u32_e32 v194, s12, v141
	v_add_u32_e32 v70, v194, v143
	v_add_u32_e32 v74, v194, v144
	ds_read_b128 v[66:69], v70
	ds_read_b128 v[70:73], v70 offset:8192
	ds_read_b128 v[160:163], v74
	ds_read_b128 v[164:167], v74 offset:8192
	v_add_u32_e32 v74, v194, v145
	ds_read_b128 v[168:171], v74
	ds_read_b128 v[172:175], v74 offset:8192
	v_add_u32_e32 v74, v194, v146
	ds_read_b128 v[186:189], v74 offset:8192
	ds_read_b128 v[190:193], v74
	s_waitcnt lgkmcnt(0)
	v_mfma_f32_32x32x16_bf16 v[82:97], v[66:69], v[98:101], 0
	v_mfma_f32_32x32x16_bf16 v[66:81], v[70:73], v[98:101], 0
	v_mfma_f32_32x32x16_bf16 v[82:97], v[160:163], v[102:105], v[82:97]
	v_mfma_f32_32x32x16_bf16 v[66:81], v[164:167], v[102:105], v[66:81]
	v_mfma_f32_32x32x16_bf16 v[82:97], v[168:171], v[106:109], v[82:97]
	v_mfma_f32_32x32x16_bf16 v[66:81], v[172:175], v[106:109], v[66:81]
	v_mfma_f32_32x32x16_bf16 v[82:97], v[190:193], v[110:113], v[82:97]
	v_mfma_f32_32x32x16_bf16 v[66:81], v[186:189], v[110:113], v[66:81]
	v_add_u32_e32 v164, v194, v147
	v_add_u32_e32 v172, v194, v148
	v_add_u32_e32 v190, v194, v149
	v_add_u32_e32 v198, v194, v150
	ds_read_b128 v[160:163], v164
	ds_read_b128 v[164:167], v164 offset:8192
	ds_read_b128 v[168:171], v172
	ds_read_b128 v[172:175], v172 offset:8192
	ds_read_b128 v[186:189], v190
	ds_read_b128 v[190:193], v190 offset:8192
	ds_read_b128 v[194:197], v198 offset:8192
	ds_read_b128 v[206:209], v198
	s_waitcnt lgkmcnt(0)
	v_mfma_f32_32x32x16_bf16 v[82:97], v[160:163], v[114:117], v[82:97]
	v_mfma_f32_32x32x16_bf16 v[66:81], v[164:167], v[114:117], v[66:81]
	v_mfma_f32_32x32x16_bf16 v[82:97], v[168:171], v[118:121], v[82:97]
	v_mfma_f32_32x32x16_bf16 v[66:81], v[172:175], v[118:121], v[66:81]
	v_mfma_f32_32x32x16_bf16 v[82:97], v[186:189], v[122:125], v[82:97]
	v_mfma_f32_32x32x16_bf16 v[66:81], v[190:193], v[122:125], v[66:81]
	v_mfma_f32_32x32x16_bf16 v[82:97], v[206:209], v[126:129], v[82:97]
	v_mfma_f32_32x32x16_bf16 v[66:81], v[194:197], v[126:129], v[66:81]
	v_bfe_i32 v160, v185, 0, 1
	v_bfe_i32 v161, v185, 1, 1
	v_bfe_i32 v162, v185, 2, 1
	v_bfe_i32 v163, v185, 3, 1
	v_bfe_i32 v164, v185, 8, 1
	v_bfe_i32 v165, v185, 9, 1
	v_bfe_i32 v166, v185, 10, 1
	v_bfe_i32 v167, v185, 11, 1
	v_bfe_i32 v168, v185, 16, 1
	v_bfe_i32 v169, v185, 17, 1
	v_bfe_i32 v170, v185, 18, 1
	v_bfe_i32 v171, v185, 19, 1
	v_bfe_i32 v172, v185, 24, 1
	v_bfe_i32 v173, v185, 25, 1
	v_bfe_i32 v174, v185, 26, 1
	v_bfe_i32 v175, v185, 27, 1
	v_bfe_i32 v186, v0, 0, 1
	v_bfe_i32 v187, v0, 1, 1
	v_bfe_i32 v188, v0, 2, 1
	v_bfe_i32 v189, v0, 3, 1
	v_bfe_i32 v190, v0, 8, 1
	v_bfe_i32 v191, v0, 9, 1
	v_bfe_i32 v192, v0, 10, 1
	v_bfe_i32 v193, v0, 11, 1
	v_bfe_i32 v194, v0, 16, 1
	v_bfe_i32 v195, v0, 17, 1
	v_bfe_i32 v196, v0, 18, 1
	v_bfe_i32 v197, v0, 19, 1
	v_bfe_i32 v198, v0, 24, 1
	v_bfe_i32 v199, v0, 25, 1
	v_bfe_i32 v206, v0, 26, 1
	v_bfe_i32 v207, v0, 27, 1
	v_bfi_b32 v82, v160, v82, v215
	v_bfi_b32 v83, v161, v83, v215
	v_bfi_b32 v84, v162, v84, v215
	v_bfi_b32 v85, v163, v85, v215
	v_bfi_b32 v86, v164, v86, v215
	v_bfi_b32 v87, v165, v87, v215
	v_bfi_b32 v88, v166, v88, v215
	v_bfi_b32 v89, v167, v89, v215
	v_bfi_b32 v90, v168, v90, v215
	v_bfi_b32 v91, v169, v91, v215
	v_bfi_b32 v92, v170, v92, v215
	v_bfi_b32 v93, v171, v93, v215
	v_bfi_b32 v94, v172, v94, v215
	v_bfi_b32 v95, v173, v95, v215
	v_bfi_b32 v96, v174, v96, v215
	v_bfi_b32 v97, v175, v97, v215
	v_bfi_b32 v66, v186, v66, v215
	v_bfi_b32 v67, v187, v67, v215
	v_bfi_b32 v68, v188, v68, v215
	v_bfi_b32 v69, v189, v69, v215
	v_bfi_b32 v70, v190, v70, v215
	v_bfi_b32 v71, v191, v71, v215
	v_bfi_b32 v72, v192, v72, v215
	v_bfi_b32 v73, v193, v73, v215
	v_bfi_b32 v74, v194, v74, v215
	v_bfi_b32 v75, v195, v75, v215
	v_bfi_b32 v76, v196, v76, v215
	v_bfi_b32 v77, v197, v77, v215
	v_bfi_b32 v78, v198, v78, v215
	v_bfi_b32 v79, v199, v79, v215
	v_bfi_b32 v80, v206, v80, v215
	v_bfi_b32 v81, v207, v81, v215
	v_max3_f32 v160, v82, v83, v84
	v_max3_f32 v161, v85, v86, v87
	v_max3_f32 v162, v88, v89, v90
	v_max3_f32 v163, v91, v92, v93
	v_max3_f32 v164, v94, v95, v96
	v_max3_f32 v165, v97, v66, v67
	v_max3_f32 v166, v68, v69, v70
	v_max3_f32 v167, v71, v72, v73
	v_max3_f32 v168, v74, v75, v76
	v_max3_f32 v169, v77, v78, v79
	v_max3_f32 v160, v160, v161, v162
	v_max3_f32 v163, v163, v164, v165
	v_max3_f32 v166, v166, v167, v168
	v_max3_f32 v169, v169, v80, v81
	v_max3_f32 v160, v160, v163, v166
	v_max_f32_e32 v160, v160, v169
	v_mov_b32_e32 v161, v160
	s_nop 1
	v_permlane32_swap_b32_e32 v160, v161
	v_max3_f32 v162, v184, v160, v161
	v_max_f32_e32 v162, s97, v162
	v_sub_f32_e32 v163, v162, v184
	v_cmp_lt_f32_e32 vcc, 8.0, v163
	s_nop 1
	v_cndmask_b32_e32 v162, v184, v162, vcc
	v_mov_b32_e32 v201, v162
	v_sub_f32_e32 v200, v184, v162
	v_exp_f32_e32 v200, v200
	v_add_u32_e32 v210, s12, v142
	v_add3_u32 v211, v210, v151, v154
	v_add3_u32 v212, v210, v151, v177
	v_add3_u32 v213, v210, v151, v178
	v_add3_u32 v216, v210, v151, v179
	v_add3_u32 v217, v210, v151, v180
	v_add3_u32 v252, v210, v151, v181
	v_add3_u32 v253, v210, v151, v182
	v_add3_u32 v210, v210, v151, v152
	v_cmp_neq_f32_e32 vcc, 1.0, v200
	s_cbranch_vccz .Ldsa_nors
	v_pk_mul_f32 v[64:65], v[64:65], v[200:201] op_sel_hi:[1,0]
	v_pk_mul_f32 v[62:63], v[62:63], v[200:201] op_sel_hi:[1,0]
	v_pk_mul_f32 v[60:61], v[60:61], v[200:201] op_sel_hi:[1,0]
	v_pk_mul_f32 v[58:59], v[58:59], v[200:201] op_sel_hi:[1,0]
	v_pk_mul_f32 v[56:57], v[56:57], v[200:201] op_sel_hi:[1,0]
	v_pk_mul_f32 v[54:55], v[54:55], v[200:201] op_sel_hi:[1,0]
	v_pk_mul_f32 v[52:53], v[52:53], v[200:201] op_sel_hi:[1,0]
	v_pk_mul_f32 v[50:51], v[50:51], v[200:201] op_sel_hi:[1,0]
	v_pk_mul_f32 v[48:49], v[48:49], v[200:201] op_sel_hi:[1,0]
	v_pk_mul_f32 v[46:47], v[46:47], v[200:201] op_sel_hi:[1,0]
	v_pk_mul_f32 v[44:45], v[44:45], v[200:201] op_sel_hi:[1,0]
	v_pk_mul_f32 v[42:43], v[42:43], v[200:201] op_sel_hi:[1,0]
	v_pk_mul_f32 v[40:41], v[40:41], v[200:201] op_sel_hi:[1,0]
	v_pk_mul_f32 v[38:39], v[38:39], v[200:201] op_sel_hi:[1,0]
	v_pk_mul_f32 v[36:37], v[36:37], v[200:201] op_sel_hi:[1,0]
	v_pk_mul_f32 v[34:35], v[34:35], v[200:201] op_sel_hi:[1,0]
	v_pk_mul_f32 v[32:33], v[32:33], v[200:201] op_sel_hi:[1,0]
	v_pk_mul_f32 v[30:31], v[30:31], v[200:201] op_sel_hi:[1,0]
	v_pk_mul_f32 v[28:29], v[28:29], v[200:201] op_sel_hi:[1,0]
	v_pk_mul_f32 v[26:27], v[26:27], v[200:201] op_sel_hi:[1,0]
	v_pk_mul_f32 v[24:25], v[24:25], v[200:201] op_sel_hi:[1,0]
	v_pk_mul_f32 v[22:23], v[22:23], v[200:201] op_sel_hi:[1,0]
	v_pk_mul_f32 v[20:21], v[20:21], v[200:201] op_sel_hi:[1,0]
	v_pk_mul_f32 v[18:19], v[18:19], v[200:201] op_sel_hi:[1,0]
	v_pk_mul_f32 v[16:17], v[16:17], v[200:201] op_sel_hi:[1,0]
	v_pk_mul_f32 v[14:15], v[14:15], v[200:201] op_sel_hi:[1,0]
	v_pk_mul_f32 v[12:13], v[12:13], v[200:201] op_sel_hi:[1,0]
	v_pk_mul_f32 v[10:11], v[10:11], v[200:201] op_sel_hi:[1,0]
	v_pk_mul_f32 v[8:9], v[8:9], v[200:201] op_sel_hi:[1,0]
	v_pk_mul_f32 v[6:7], v[6:7], v[200:201] op_sel_hi:[1,0]
	v_pk_mul_f32 v[4:5], v[4:5], v[200:201] op_sel_hi:[1,0]
	v_pk_mul_f32 v[2:3], v[2:3], v[200:201] op_sel_hi:[1,0]
; __device__ __forceinline__ unsigned cvtpk(float lo, float hi) { unsigned r; asm("v_cvt_pk_bf16_f32 %0, %1, %2" : "=v"(r) : "v"(lo), "v"(hi)); return r; }
; template <bool MASKED>
; __device__ __forceinline__ void softmax_tile(f32x16& s0, f32x16& s1, float& m, float& l, float& alpha, unsigned mlo, unsigned mhi, bf16x8 (&pk)[4]) {
;     ...
;     for (int r = 0; r < 16; ++r) {
;         float p0 = __builtin_amdgcn_exp2f(s0[r] - mn), p1 = __builtin_amdgcn_exp2f(s1[r] - mn);
;         if (MASKED) { if (s0[r] <= -1e29f) p0 = 0.f; if (s1[r] <= -1e29f) p1 = 0.f; }
;         s0[r] = p0; s1[r] = p1; sum += p0 + p1;
;     }
;     l = l * alpha + sum;
; #pragma unroll
;     for (int k2 = 0; k2 < 2; ++k2) {
;         u32x4 a, b;
;         a.x = cvtpk(s0[8 * k2 + 0], s0[8 * k2 + 1]); a.y = cvtpk(s0[8 * k2 + 2], s0[8 * k2 + 3]); a.z = cvtpk(s0[8 * k2 + 4], s0[8 * k2 + 5]); a.w = cvtpk(s0[8 * k2 + 6], s0[8 * k2 + 7]);
;         b.x = cvtpk(s1[8 * k2 + 0], s1[8 * k2 + 1]); b.y = cvtpk(s1[8 * k2 + 2], s1[8 * k2 + 3]); b.z = cvtpk(s1[8 * k2 + 4], s1[8 * k2 + 5]); b.w = cvtpk(s1[8 * k2 + 6], s1[8 * k2 + 7]);
;         pk[k2] = __builtin_bit_cast(bf16x8, a); pk[2 + k2] = __builtin_bit_cast(bf16x8, b);
;     }
.Ldsa_nors:
	ds_read_b64_tr_b16 v[160:161], v210
	ds_read_b64_tr_b16 v[162:163], v211 offset:2048
	ds_read_b64_tr_b16 v[164:165], v212
	ds_read_b64_tr_b16 v[166:167], v213 offset:2048
	ds_read_b64_tr_b16 v[168:169], v216
	ds_read_b64_tr_b16 v[170:171], v217 offset:2048
	ds_read_b64_tr_b16 v[172:173], v252
	ds_read_b64_tr_b16 v[174:175], v253 offset:2048
	ds_read_b64_tr_b16 v[186:187], v210 offset:4096
	ds_read_b64_tr_b16 v[188:189], v211 offset:6144
	ds_read_b64_tr_b16 v[190:191], v212 offset:4096
	ds_read_b64_tr_b16 v[192:193], v213 offset:6144
	ds_read_b64_tr_b16 v[194:195], v216 offset:4096
	ds_read_b64_tr_b16 v[196:197], v217 offset:6144
	ds_read_b64_tr_b16 v[206:207], v252 offset:4096
	ds_read_b64_tr_b16 v[208:209], v253 offset:6144
	v_sub_f32_e32 v82, v82, v201
	v_sub_f32_e32 v83, v83, v201
	v_sub_f32_e32 v84, v84, v201
	v_sub_f32_e32 v85, v85, v201
	v_sub_f32_e32 v86, v86, v201
	v_sub_f32_e32 v87, v87, v201
	v_sub_f32_e32 v88, v88, v201
	v_sub_f32_e32 v89, v89, v201
	v_sub_f32_e32 v90, v90, v201
	v_sub_f32_e32 v91, v91, v201
	v_sub_f32_e32 v92, v92, v201
	v_sub_f32_e32 v93, v93, v201
	v_sub_f32_e32 v94, v94, v201
	v_sub_f32_e32 v95, v95, v201
	v_sub_f32_e32 v96, v96, v201
	v_sub_f32_e32 v97, v97, v201
	v_exp_f32_e32 v82, v82
	v_exp_f32_e32 v83, v83
	v_exp_f32_e32 v84, v84
	v_exp_f32_e32 v85, v85
	v_exp_f32_e32 v86, v86
	v_exp_f32_e32 v87, v87
	v_exp_f32_e32 v88, v88
	v_exp_f32_e32 v89, v89
	v_exp_f32_e32 v90, v90
	v_exp_f32_e32 v91, v91
	v_exp_f32_e32 v92, v92
	v_exp_f32_e32 v93, v93
	v_exp_f32_e32 v94, v94
	v_exp_f32_e32 v95, v95
	v_exp_f32_e32 v96, v96
	v_exp_f32_e32 v97, v97
	v_pk_add_f32 v[198:199], v[82:83], v[84:85]
	v_pk_add_f32 v[198:199], v[198:199], v[86:87]
	v_pk_add_f32 v[198:199], v[198:199], v[88:89]
	v_pk_add_f32 v[198:199], v[198:199], v[90:91]
	v_pk_add_f32 v[198:199], v[198:199], v[92:93]
	v_pk_add_f32 v[198:199], v[198:199], v[94:95]
	v_pk_add_f32 v[198:199], v[198:199], v[96:97]
	v_cvt_pk_bf16_f32 v82, v82, v83
	v_cvt_pk_bf16_f32 v83, v84, v85
	v_cvt_pk_bf16_f32 v84, v86, v87
	v_cvt_pk_bf16_f32 v85, v88, v89
	v_cvt_pk_bf16_f32 v86, v90, v91
	v_cvt_pk_bf16_f32 v87, v92, v93
	v_cvt_pk_bf16_f32 v88, v94, v95
	v_cvt_pk_bf16_f32 v89, v96, v97
	ds_read_b64_tr_b16 v[236:237], v210 offset:8192
	ds_read_b64_tr_b16 v[238:239], v211 offset:10240
	ds_read_b64_tr_b16 v[240:241], v212 offset:8192
	ds_read_b64_tr_b16 v[242:243], v213 offset:10240
	ds_read_b64_tr_b16 v[244:245], v216 offset:8192
	ds_read_b64_tr_b16 v[246:247], v217 offset:10240
	ds_read_b64_tr_b16 v[90:91], v252 offset:8192
	ds_read_b64_tr_b16 v[92:93], v253 offset:10240
	ds_read_b64_tr_b16 v[94:95], v210 offset:12288
	ds_read_b64_tr_b16 v[96:97], v211 offset:14336
	s_waitcnt lgkmcnt(10)
	s_nop 0
	v_mfma_f32_32x32x16_bf16 v[50:65], v[160:163], v[82:85], v[50:65]
	v_sub_f32_e32 v66, v66, v201
	v_sub_f32_e32 v67, v67, v201
	v_sub_f32_e32 v68, v68, v201
	v_sub_f32_e32 v69, v69, v201
	v_sub_f32_e32 v70, v70, v201
	v_sub_f32_e32 v71, v71, v201
	v_mfma_f32_32x32x16_bf16 v[34:49], v[164:167], v[82:85], v[34:49]
	ds_read_b64_tr_b16 v[160:161], v212 offset:12288
	ds_read_b64_tr_b16 v[162:163], v213 offset:14336
	v_sub_f32_e32 v72, v72, v201
	v_sub_f32_e32 v73, v73, v201
	v_sub_f32_e32 v74, v74, v201
	v_sub_f32_e32 v75, v75, v201
	v_sub_f32_e32 v76, v76, v201
	v_sub_f32_e32 v77, v77, v201
	v_mfma_f32_32x32x16_bf16 v[18:33], v[168:171], v[82:85], v[18:33]
	ds_read_b64_tr_b16 v[164:165], v216 offset:12288
	ds_read_b64_tr_b16 v[166:167], v217 offset:14336
	v_sub_f32_e32 v78, v78, v201
	v_sub_f32_e32 v79, v79, v201
	v_sub_f32_e32 v80, v80, v201
	v_sub_f32_e32 v81, v81, v201
	v_exp_f32_e32 v66, v66
	v_exp_f32_e32 v67, v67
	v_mfma_f32_32x32x16_bf16 v[2:17], v[172:175], v[82:85], v[2:17]
	ds_read_b64_tr_b16 v[168:169], v252 offset:12288
	ds_read_b64_tr_b16 v[170:171], v253 offset:14336
	v_exp_f32_e32 v68, v68
	v_exp_f32_e32 v69, v69
	v_exp_f32_e32 v70, v70
	v_exp_f32_e32 v71, v71
	v_exp_f32_e32 v72, v72
	v_exp_f32_e32 v73, v73
	v_mfma_f32_32x32x16_bf16 v[50:65], v[186:189], v[86:89], v[50:65]
	v_exp_f32_e32 v74, v74
	v_exp_f32_e32 v75, v75
	v_exp_f32_e32 v76, v76
	v_exp_f32_e32 v77, v77
	v_exp_f32_e32 v78, v78
	v_exp_f32_e32 v79, v79
	v_mfma_f32_32x32x16_bf16 v[34:49], v[190:193], v[86:89], v[34:49]
	v_exp_f32_e32 v80, v80
	v_exp_f32_e32 v81, v81
	v_pk_add_f32 v[248:249], v[66:67], v[68:69]
	v_pk_add_f32 v[248:249], v[248:249], v[70:71]
	v_pk_add_f32 v[248:249], v[248:249], v[72:73]
	v_pk_add_f32 v[248:249], v[248:249], v[74:75]
	v_mfma_f32_32x32x16_bf16 v[18:33], v[194:197], v[86:89], v[18:33]
	v_pk_add_f32 v[248:249], v[248:249], v[76:77]
	v_pk_add_f32 v[248:249], v[248:249], v[78:79]
	v_pk_add_f32 v[248:249], v[248:249], v[80:81]
	v_cvt_pk_bf16_f32 v66, v66, v67
	v_cvt_pk_bf16_f32 v67, v68, v69
	v_cvt_pk_bf16_f32 v68, v70, v71
	v_mfma_f32_32x32x16_bf16 v[2:17], v[206:209], v[86:89], v[2:17]
	v_cvt_pk_bf16_f32 v69, v72, v73
	v_cvt_pk_bf16_f32 v70, v74, v75
	v_cvt_pk_bf16_f32 v71, v76, v77
	v_cvt_pk_bf16_f32 v72, v78, v79
	v_cvt_pk_bf16_f32 v73, v80, v81
	s_waitcnt lgkmcnt(0)
	s_nop 0
	v_mfma_f32_32x32x16_bf16 v[50:65], v[236:239], v[66:69], v[50:65]
	v_mfma_f32_32x32x16_bf16 v[34:49], v[240:243], v[66:69], v[34:49]
	v_mfma_f32_32x32x16_bf16 v[18:33], v[244:247], v[66:69], v[18:33]
	v_mfma_f32_32x32x16_bf16 v[2:17], v[90:93], v[66:69], v[2:17]
	v_pk_add_f32 v[198:199], v[198:199], v[248:249]
	v_mfma_f32_32x32x16_bf16 v[50:65], v[94:97], v[70:73], v[50:65]
	v_add_f32_e32 v198, v198, v199
	v_mfma_f32_32x32x16_bf16 v[34:49], v[160:163], v[70:73], v[34:49]
	v_fmac_f32_e32 v198, v183, v200
	v_mfma_f32_32x32x16_bf16 v[18:33], v[164:167], v[70:73], v[18:33]
	v_mov_b32_e32 v83, v198
	v_mfma_f32_32x32x16_bf16 v[2:17], v[168:171], v[70:73], v[2:17]
	v_mov_b32_e32 v82, v201
	v_mov_b32_e32 v183, v83
	s_andn2_b64 vcc, exec, s[0:1]
	s_mov_b64 s[0:1], -1
	s_cbranch_vccz .LBB0_1181
	s_branch .LBB0_1182
